# non-temporal loads/stores for one-shot weight conversion stream in prologue
# speedup vs baseline: 1.0168x; 1.0011x over previous
; #define LDS_WAIT() asm volatile("s_waitcnt lgkmcnt(0)" ::: "memory")
;     if (ldt == 0) ldt = K;
;     const int nblk = N / 32, kb = item / nblk, nb = item % nblk, k0 = 64 * kb, n0 = 32 * nb;
; #pragma unroll 8
;     for (int i = 0; i < 32; ++i) { const int kk = 2 * i + (lane >> 5); scr[kk * 33 + (lane & 31)] = W[(size_t)(k0 + kk) * N + n0 + (lane & 31)]; }
;     LDS_WAIT(); asm volatile("" ::: "memory");
.LBB0_21:
	s_lshl_b32 s36, s33, 1
	s_lshl_b32 s37, s34, 1
	v_or_b32_e32 v9, s37, v2
	s_add_i32 s38, s36, 4
	s_add_i32 s39, s37, 4
	s_add_i32 s43, s37, 8
	v_add_u32_e32 v4, s6, v9
	v_or_b32_e32 v11, s38, v1
	v_or_b32_e32 v23, s39, v2
	v_mov_b32_e32 v21, v5
	v_or_b32_e32 v0, s36, v1
	s_add_i32 s45, s37, 12
	v_or_b32_e32 v43, s43, v2
	v_lshlrev_b64 v[36:37], 11, v[4:5]
	v_add_u32_e32 v20, s13, v11
	v_add_u32_e32 v4, s6, v23
	v_mov_b32_e32 v19, v5
	s_add_i32 s42, s36, 8
	s_add_i32 s44, s36, 12
	s_add_i32 s47, s37, 16
	v_add_u32_e32 v18, s13, v0
	v_or_b32_e32 v45, s45, v2
	v_lshlrev_b64 v[20:21], 11, v[20:21]
	v_lshlrev_b64 v[38:39], 11, v[4:5]
	v_add_u32_e32 v4, s6, v43
	s_add_i32 s49, s37, 20
	v_or_b32_e32 v42, s42, v1
	v_or_b32_e32 v44, s44, v1
	v_or_b32_e32 v47, s47, v2
	v_lshlrev_b64 v[18:19], 11, v[18:19]
	v_lshl_add_u64 v[36:37], v[12:13], 0, v[36:37]
	v_lshl_add_u64 v[20:21], v[12:13], 0, v[20:21]
	v_lshlrev_b64 v[40:41], 11, v[4:5]
	v_add_u32_e32 v4, s6, v45
	v_mov_b32_e32 v25, v5
	v_mov_b32_e32 v27, v5
	s_add_i32 s46, s36, 16
	s_add_i32 s48, s36, 20
	s_add_i32 s51, s37, 24
	v_or_b32_e32 v49, s49, v2
	v_add_u32_e32 v24, s13, v42
	v_add_u32_e32 v26, s13, v44
	v_lshl_add_u64 v[18:19], v[12:13], 0, v[18:19]
	v_lshl_add_u64 v[38:39], v[12:13], 0, v[38:39]
	global_load_dword v54, v[36:37], off nt
	global_load_dword v55, v[18:19], off nt
	global_load_dword v56, v[38:39], off nt
	global_load_dword v57, v[20:21], off nt
	v_lshlrev_b64 v[20:21], 11, v[4:5]
	v_add_u32_e32 v4, s6, v47
	s_add_i32 s50, s36, 24
	s_add_i32 s36, s36, 28
	s_add_i32 s37, s37, 28
	v_or_b32_e32 v46, s46, v1
	v_or_b32_e32 v48, s48, v1
	v_or_b32_e32 v51, s51, v2
	v_lshlrev_b64 v[24:25], 11, v[24:25]
	v_lshlrev_b64 v[26:27], 11, v[26:27]
	v_lshl_add_u64 v[18:19], v[12:13], 0, v[40:41]
	v_lshl_add_u64 v[20:21], v[12:13], 0, v[20:21]
	v_lshlrev_b64 v[36:37], 11, v[4:5]
	v_add_u32_e32 v4, s6, v49
	v_mov_b32_e32 v29, v5
	v_mov_b32_e32 v31, v5
	v_or_b32_e32 v50, s50, v1
	v_or_b32_e32 v52, s36, v1
	v_or_b32_e32 v53, s37, v2
	v_add_u32_e32 v28, s13, v46
	v_add_u32_e32 v30, s13, v48
	v_lshl_add_u64 v[24:25], v[12:13], 0, v[24:25]
	v_lshl_add_u64 v[26:27], v[12:13], 0, v[26:27]
	global_load_dword v58, v[18:19], off nt
	global_load_dword v59, v[24:25], off nt
	global_load_dword v60, v[20:21], off nt
	global_load_dword v61, v[26:27], off nt
	v_lshlrev_b64 v[20:21], 11, v[4:5]
	v_add_u32_e32 v4, s6, v51
	v_mov_b32_e32 v33, v5
	v_mov_b32_e32 v35, v5
	v_add_u32_e32 v32, s13, v50
	v_add_u32_e32 v34, s13, v52
	v_lshlrev_b64 v[28:29], 11, v[28:29]
	v_lshlrev_b64 v[30:31], 11, v[30:31]
	v_lshl_add_u64 v[18:19], v[12:13], 0, v[36:37]
	v_lshl_add_u64 v[20:21], v[12:13], 0, v[20:21]
	v_lshlrev_b64 v[24:25], 11, v[4:5]
	v_add_u32_e32 v4, s6, v53
	v_lshlrev_b64 v[32:33], 11, v[32:33]
	v_lshlrev_b64 v[34:35], 11, v[34:35]
	v_lshl_add_u64 v[28:29], v[12:13], 0, v[28:29]
	v_lshl_add_u64 v[30:31], v[12:13], 0, v[30:31]
	global_load_dword v62, v[18:19], off nt
	global_load_dword v63, v[28:29], off nt
	global_load_dword v64, v[20:21], off nt
	global_load_dword v65, v[30:31], off nt
	v_lshl_add_u64 v[18:19], v[12:13], 0, v[24:25]
	v_lshlrev_b64 v[20:21], 11, v[4:5]
	v_lshl_add_u64 v[32:33], v[12:13], 0, v[32:33]
	v_lshl_add_u64 v[34:35], v[12:13], 0, v[34:35]
	v_lshl_add_u64 v[20:21], v[12:13], 0, v[20:21]
	global_load_dword v4, v[18:19], off nt
	global_load_dword v66, v[32:33], off nt
	global_load_dword v67, v[20:21], off nt
	global_load_dword v68, v[34:35], off nt
	s_add_i32 s34, s34, 16
	s_add_i32 s33, s33, 16
	s_add_i32 s35, s35, -16
	v_mad_u64_u32 v[18:19], s[36:37], v9, s29, v[6:7]
	s_cmp_lg_u32 s35, 0
	v_mad_u64_u32 v[20:21], s[36:37], v0, s29, v[6:7]
	v_mad_u64_u32 v[24:25], s[36:37], v23, s29, v[6:7]
	v_mad_u64_u32 v[26:27], s[36:37], v11, s29, v[6:7]
	v_mad_u64_u32 v[28:29], s[36:37], v43, s29, v[6:7]
	v_mad_u64_u32 v[30:31], s[36:37], v42, s29, v[6:7]
	v_mad_u64_u32 v[32:33], s[36:37], v45, s29, v[6:7]
	v_mad_u64_u32 v[34:35], s[36:37], v44, s29, v[6:7]
	v_mad_u64_u32 v[36:37], s[36:37], v47, s29, v[6:7]
	v_mad_u64_u32 v[38:39], s[36:37], v46, s29, v[6:7]
	v_mad_u64_u32 v[40:41], s[36:37], v49, s29, v[6:7]
	v_mad_u64_u32 v[42:43], s[36:37], v48, s29, v[6:7]
	v_mad_u64_u32 v[44:45], s[36:37], v51, s29, v[6:7]
	v_mad_u64_u32 v[46:47], s[36:37], v50, s29, v[6:7]
	v_mad_u64_u32 v[48:49], s[36:37], v53, s29, v[6:7]
	v_mad_u64_u32 v[50:51], s[36:37], v52, s29, v[6:7]
	s_waitcnt vmcnt(15)
	ds_write_b32 v18, v54
	s_waitcnt vmcnt(14)
	ds_write_b32 v20, v55
	s_waitcnt vmcnt(13)
	ds_write_b32 v24, v56
	s_waitcnt vmcnt(12)
	ds_write_b32 v26, v57
	s_waitcnt vmcnt(11)
	ds_write_b32 v28, v58
	s_waitcnt vmcnt(10)
	ds_write_b32 v30, v59
	s_waitcnt vmcnt(9)
	ds_write_b32 v32, v60
	s_waitcnt vmcnt(8)
	ds_write_b32 v34, v61
	s_waitcnt vmcnt(7)
	ds_write_b32 v36, v62
	s_waitcnt vmcnt(6)
	ds_write_b32 v38, v63
	s_waitcnt vmcnt(5)
	ds_write_b32 v40, v64
	s_waitcnt vmcnt(4)
	ds_write_b32 v42, v65
	s_waitcnt vmcnt(3)
	ds_write_b32 v44, v4
	s_waitcnt vmcnt(2)
	ds_write_b32 v46, v66
	s_waitcnt vmcnt(1)
	ds_write_b32 v48, v67
	s_waitcnt vmcnt(0)
	ds_write_b32 v50, v68
	s_cbranch_scc1 .LBB0_21
; #define GAS __attribute__((address_space(1)))
; #define LAS __attribute__((address_space(3)))
; #define LDS_WAIT() asm volatile("s_waitcnt lgkmcnt(0)" ::: "memory")
; __device__ __forceinline__ unsigned pk2(float lo, float hi) { return pg8::pkc(lo, hi); }
;     ...
;     const int c = lane & 7;
; #pragma unroll
;     for (int j = 0; j < 4; ++j) { const int n = (lane >> 3) + 8 * j; const LAS float* s = scr + (8 * c) * 33 + n;
;         v4u o; o.x = pk2(s[0 * 33], s[1 * 33]); o.y = pk2(s[2 * 33], s[3 * 33]); o.z = pk2(s[4 * 33], s[5 * 33]); o.w = pk2(s[6 * 33], s[7 * 33]);
;         *(GAS v4u*)(WT + (size_t)(n0 + n) * ldt + k0 + 8 * c) = o; }
;     LDS_WAIT(); asm volatile("" ::: "memory");
	s_waitcnt lgkmcnt(0)
	s_lshl_b64 s[10:11], s[10:11], 1
	s_add_u32 s10, s23, s10
	ds_read2_b32 v[12:13], v14 offset0:33 offset1:41
	ds_read2_b32 v[24:25], v14 offset1:8
	ds_read2_b32 v[26:27], v14 offset0:66 offset1:74
	ds_read2_b32 v[28:29], v14 offset0:99 offset1:107
	ds_read2_b32 v[30:31], v14 offset0:132 offset1:140
	ds_read2_b32 v[32:33], v14 offset0:165 offset1:173
	ds_read2_b32 v[34:35], v14 offset0:198 offset1:206
	ds_read2_b32 v[36:37], v14 offset0:231 offset1:239
	s_addc_u32 s11, s24, s11
	s_and_b32 s12, 0xffff, s12
	s_lshl_b32 s6, s6, 1
	s_add_u32 s10, s10, s6
	s_addc_u32 s11, s11, 0
	v_mov_b32_e32 v11, v5
	v_or_b32_e32 v0, s12, v3
	v_lshl_add_u64 v[38:39], s[10:11], 0, v[10:11]
	v_lshlrev_b32_e32 v4, 10, v0
	s_waitcnt lgkmcnt(6)
	v_cvt_pk_bf16_f32 v18, v24, v12
	s_waitcnt lgkmcnt(4)
	v_cvt_pk_bf16_f32 v19, v26, v28
	s_waitcnt lgkmcnt(2)
	v_cvt_pk_bf16_f32 v20, v30, v32
	s_waitcnt lgkmcnt(0)
	v_cvt_pk_bf16_f32 v21, v34, v36
	v_lshl_add_u64 v[40:41], v[38:39], 0, v[4:5]
	global_store_dwordx4 v[40:41], v[18:21], off nt
	v_or_b32_e32 v0, s12, v15
	v_lshlrev_b32_e32 v4, 10, v0
	v_cvt_pk_bf16_f32 v18, v25, v13
	v_cvt_pk_bf16_f32 v19, v27, v29
	v_cvt_pk_bf16_f32 v20, v31, v33
	v_cvt_pk_bf16_f32 v21, v35, v37
	ds_read2_b32 v[24:25], v14 offset0:49 offset1:57
	ds_read2_b32 v[26:27], v14 offset0:16 offset1:24
	ds_read2_b32 v[28:29], v14 offset0:82 offset1:90
	ds_read2_b32 v[30:31], v14 offset0:115 offset1:123
	ds_read2_b32 v[32:33], v14 offset0:148 offset1:156
	ds_read2_b32 v[34:35], v14 offset0:181 offset1:189
	ds_read2_b32 v[36:37], v14 offset0:214 offset1:222
	ds_read2_b32 v[40:41], v14 offset0:247 offset1:255
	v_or_b32_e32 v0, s12, v16
	v_lshl_add_u64 v[12:13], v[38:39], 0, v[4:5]
	v_lshlrev_b32_e32 v4, 10, v0
	v_or_b32_e32 v0, s12, v17
	global_store_dwordx4 v[12:13], v[18:21], off nt
	v_lshl_add_u64 v[12:13], v[38:39], 0, v[4:5]
	v_lshlrev_b32_e32 v4, 10, v0
	s_waitcnt lgkmcnt(6)
	v_cvt_pk_bf16_f32 v18, v26, v24
	s_waitcnt lgkmcnt(4)
	v_cvt_pk_bf16_f32 v19, v28, v30
	s_waitcnt lgkmcnt(2)
	v_cvt_pk_bf16_f32 v20, v32, v34
	s_waitcnt lgkmcnt(0)
	v_cvt_pk_bf16_f32 v21, v36, v40
	global_store_dwordx4 v[12:13], v[18:21], off nt
	v_lshl_add_u64 v[12:13], v[38:39], 0, v[4:5]
	s_mov_b64 s[10:11], 0
	v_cvt_pk_bf16_f32 v18, v27, v25
	v_cvt_pk_bf16_f32 v19, v29, v31
	v_cvt_pk_bf16_f32 v20, v33, v35
	v_cvt_pk_bf16_f32 v21, v37, v41
	global_store_dwordx4 v[12:13], v[18:21], off nt
	s_waitcnt lgkmcnt(0)

; #define LDS_WAIT() asm volatile("s_waitcnt lgkmcnt(0)" ::: "memory")
;     if (ldt == 0) ldt = K;
;     const int nblk = N / 32, kb = item / nblk, nb = item % nblk, k0 = 64 * kb, n0 = 32 * nb;
; #pragma unroll 8
;     for (int i = 0; i < 32; ++i) { const int kk = 2 * i + (lane >> 5); scr[kk * 33 + (lane & 31)] = W[(size_t)(k0 + kk) * N + n0 + (lane & 31)]; }
;     LDS_WAIT(); asm volatile("" ::: "memory");
.LBB0_25:
	s_lshl_b32 s36, s33, 1
	s_lshl_b32 s37, s34, 1
	v_or_b32_e32 v9, s37, v2
	s_add_i32 s38, s36, 4
	s_add_i32 s39, s37, 4
	s_add_i32 s43, s37, 8
	v_add_u32_e32 v4, s6, v9
	v_or_b32_e32 v11, s38, v1
	v_or_b32_e32 v23, s39, v2
	v_mov_b32_e32 v21, v5
	v_or_b32_e32 v0, s36, v1
	s_add_i32 s45, s37, 12
	v_or_b32_e32 v43, s43, v2
	v_lshlrev_b64 v[36:37], 13, v[4:5]
	v_add_u32_e32 v20, s13, v11
	v_add_u32_e32 v4, s6, v23
	v_mov_b32_e32 v19, v5
	s_add_i32 s42, s36, 8
	s_add_i32 s44, s36, 12
	s_add_i32 s47, s37, 16
	v_add_u32_e32 v18, s13, v0
	v_or_b32_e32 v45, s45, v2
	v_lshlrev_b64 v[20:21], 13, v[20:21]
	v_lshlrev_b64 v[38:39], 13, v[4:5]
	v_add_u32_e32 v4, s6, v43
	s_add_i32 s49, s37, 20
	v_or_b32_e32 v42, s42, v1
	v_or_b32_e32 v44, s44, v1
	v_or_b32_e32 v47, s47, v2
	v_lshlrev_b64 v[18:19], 13, v[18:19]
	v_lshl_add_u64 v[36:37], v[12:13], 0, v[36:37]
	v_lshl_add_u64 v[20:21], v[12:13], 0, v[20:21]
	v_lshlrev_b64 v[40:41], 13, v[4:5]
	v_add_u32_e32 v4, s6, v45
	v_mov_b32_e32 v25, v5
	v_mov_b32_e32 v27, v5
	s_add_i32 s46, s36, 16
	s_add_i32 s48, s36, 20
	s_add_i32 s51, s37, 24
	v_or_b32_e32 v49, s49, v2
	v_add_u32_e32 v24, s13, v42
	v_add_u32_e32 v26, s13, v44
	v_lshl_add_u64 v[18:19], v[12:13], 0, v[18:19]
	v_lshl_add_u64 v[38:39], v[12:13], 0, v[38:39]
	global_load_dword v54, v[36:37], off nt
	global_load_dword v55, v[18:19], off nt
	global_load_dword v56, v[38:39], off nt
	global_load_dword v57, v[20:21], off nt
	v_lshlrev_b64 v[20:21], 13, v[4:5]
	v_add_u32_e32 v4, s6, v47
	s_add_i32 s50, s36, 24
	s_add_i32 s36, s36, 28
	s_add_i32 s37, s37, 28
	v_or_b32_e32 v46, s46, v1
	v_or_b32_e32 v48, s48, v1
	v_or_b32_e32 v51, s51, v2
	v_lshlrev_b64 v[24:25], 13, v[24:25]
	v_lshlrev_b64 v[26:27], 13, v[26:27]
	v_lshl_add_u64 v[18:19], v[12:13], 0, v[40:41]
	v_lshl_add_u64 v[20:21], v[12:13], 0, v[20:21]
	v_lshlrev_b64 v[36:37], 13, v[4:5]
	v_add_u32_e32 v4, s6, v49
	v_mov_b32_e32 v29, v5
	v_mov_b32_e32 v31, v5
	v_or_b32_e32 v50, s50, v1
	v_or_b32_e32 v52, s36, v1
	v_or_b32_e32 v53, s37, v2
	v_add_u32_e32 v28, s13, v46
	v_add_u32_e32 v30, s13, v48
	v_lshl_add_u64 v[24:25], v[12:13], 0, v[24:25]
	v_lshl_add_u64 v[26:27], v[12:13], 0, v[26:27]
	global_load_dword v58, v[18:19], off nt
	global_load_dword v59, v[24:25], off nt
	global_load_dword v60, v[20:21], off nt
	global_load_dword v61, v[26:27], off nt
	v_lshlrev_b64 v[20:21], 13, v[4:5]
	v_add_u32_e32 v4, s6, v51
	v_mov_b32_e32 v33, v5
	v_mov_b32_e32 v35, v5
	v_add_u32_e32 v32, s13, v50
	v_add_u32_e32 v34, s13, v52
	v_lshlrev_b64 v[28:29], 13, v[28:29]
	v_lshlrev_b64 v[30:31], 13, v[30:31]
	v_lshl_add_u64 v[18:19], v[12:13], 0, v[36:37]
	v_lshl_add_u64 v[20:21], v[12:13], 0, v[20:21]
	v_lshlrev_b64 v[24:25], 13, v[4:5]
	v_add_u32_e32 v4, s6, v53
	v_lshlrev_b64 v[32:33], 13, v[32:33]
	v_lshlrev_b64 v[34:35], 13, v[34:35]
	v_lshl_add_u64 v[28:29], v[12:13], 0, v[28:29]
	v_lshl_add_u64 v[30:31], v[12:13], 0, v[30:31]
	global_load_dword v62, v[18:19], off nt
	global_load_dword v63, v[28:29], off nt
	global_load_dword v64, v[20:21], off nt
	global_load_dword v65, v[30:31], off nt
	v_lshl_add_u64 v[18:19], v[12:13], 0, v[24:25]
	v_lshlrev_b64 v[20:21], 13, v[4:5]
	v_lshl_add_u64 v[32:33], v[12:13], 0, v[32:33]
	v_lshl_add_u64 v[34:35], v[12:13], 0, v[34:35]
	v_lshl_add_u64 v[20:21], v[12:13], 0, v[20:21]
	global_load_dword v4, v[18:19], off nt
	global_load_dword v66, v[32:33], off nt
	global_load_dword v67, v[20:21], off nt
	global_load_dword v68, v[34:35], off nt
	s_add_i32 s34, s34, 16
	s_add_i32 s33, s33, 16
	s_add_i32 s35, s35, -16
	v_mad_u64_u32 v[18:19], s[36:37], v9, s29, v[6:7]
	s_cmp_lg_u32 s35, 0
	v_mad_u64_u32 v[20:21], s[36:37], v0, s29, v[6:7]
	v_mad_u64_u32 v[24:25], s[36:37], v23, s29, v[6:7]
	v_mad_u64_u32 v[26:27], s[36:37], v11, s29, v[6:7]
	v_mad_u64_u32 v[28:29], s[36:37], v43, s29, v[6:7]
	v_mad_u64_u32 v[30:31], s[36:37], v42, s29, v[6:7]
	v_mad_u64_u32 v[32:33], s[36:37], v45, s29, v[6:7]
	v_mad_u64_u32 v[34:35], s[36:37], v44, s29, v[6:7]
	v_mad_u64_u32 v[36:37], s[36:37], v47, s29, v[6:7]
	v_mad_u64_u32 v[38:39], s[36:37], v46, s29, v[6:7]
	v_mad_u64_u32 v[40:41], s[36:37], v49, s29, v[6:7]
	v_mad_u64_u32 v[42:43], s[36:37], v48, s29, v[6:7]
	v_mad_u64_u32 v[44:45], s[36:37], v51, s29, v[6:7]
	v_mad_u64_u32 v[46:47], s[36:37], v50, s29, v[6:7]
	v_mad_u64_u32 v[48:49], s[36:37], v53, s29, v[6:7]
	v_mad_u64_u32 v[50:51], s[36:37], v52, s29, v[6:7]
	s_waitcnt vmcnt(15)
	ds_write_b32 v18, v54
	s_waitcnt vmcnt(14)
	ds_write_b32 v20, v55
	s_waitcnt vmcnt(13)
	ds_write_b32 v24, v56
	s_waitcnt vmcnt(12)
	ds_write_b32 v26, v57
	s_waitcnt vmcnt(11)
	ds_write_b32 v28, v58
	s_waitcnt vmcnt(10)
	ds_write_b32 v30, v59
	s_waitcnt vmcnt(9)
	ds_write_b32 v32, v60
	s_waitcnt vmcnt(8)
	ds_write_b32 v34, v61
	s_waitcnt vmcnt(7)
	ds_write_b32 v36, v62
	s_waitcnt vmcnt(6)
	ds_write_b32 v38, v63
	s_waitcnt vmcnt(5)
	ds_write_b32 v40, v64
	s_waitcnt vmcnt(4)
	ds_write_b32 v42, v65
	s_waitcnt vmcnt(3)
	ds_write_b32 v44, v4
	s_waitcnt vmcnt(2)
	ds_write_b32 v46, v66
	s_waitcnt vmcnt(1)
	ds_write_b32 v48, v67
	s_waitcnt vmcnt(0)
	ds_write_b32 v50, v68
	s_cbranch_scc1 .LBB0_25
; #define GAS __attribute__((address_space(1)))
; #define LAS __attribute__((address_space(3)))
; #define LDS_WAIT() asm volatile("s_waitcnt lgkmcnt(0)" ::: "memory")
; __device__ __forceinline__ unsigned pk2(float lo, float hi) { return pg8::pkc(lo, hi); }
;     ...
;     const int c = lane & 7;
; #pragma unroll
;     for (int j = 0; j < 4; ++j) { const int n = (lane >> 3) + 8 * j; const LAS float* s = scr + (8 * c) * 33 + n;
;         v4u o; o.x = pk2(s[0 * 33], s[1 * 33]); o.y = pk2(s[2 * 33], s[3 * 33]); o.z = pk2(s[4 * 33], s[5 * 33]); o.w = pk2(s[6 * 33], s[7 * 33]);
;         *(GAS v4u*)(WT + (size_t)(n0 + n) * ldt + k0 + 8 * c) = o; }
;     LDS_WAIT(); asm volatile("" ::: "memory");
	s_waitcnt lgkmcnt(0)
	s_lshl_b64 s[10:11], s[10:11], 1
	s_add_u32 s10, s19, s10
	ds_read2_b32 v[12:13], v14 offset0:33 offset1:41
	ds_read2_b32 v[24:25], v14 offset1:8
	ds_read2_b32 v[26:27], v14 offset0:66 offset1:74
	ds_read2_b32 v[28:29], v14 offset0:99 offset1:107
	ds_read2_b32 v[30:31], v14 offset0:132 offset1:140
	ds_read2_b32 v[32:33], v14 offset0:165 offset1:173
	ds_read2_b32 v[34:35], v14 offset0:198 offset1:206
	ds_read2_b32 v[36:37], v14 offset0:231 offset1:239
	s_addc_u32 s11, s22, s11
	s_and_b32 s12, 0xffff, s12
	s_lshl_b32 s6, s6, 1
	s_add_u32 s10, s10, s6
	s_addc_u32 s11, s11, 0
	v_mov_b32_e32 v11, v5
	v_or_b32_e32 v0, s12, v3
	v_lshl_add_u64 v[38:39], s[10:11], 0, v[10:11]
	v_lshlrev_b32_e32 v4, 12, v0
	s_waitcnt lgkmcnt(6)
	v_cvt_pk_bf16_f32 v18, v24, v12
	s_waitcnt lgkmcnt(4)
	v_cvt_pk_bf16_f32 v19, v26, v28
	s_waitcnt lgkmcnt(2)
	v_cvt_pk_bf16_f32 v20, v30, v32
	s_waitcnt lgkmcnt(0)
	v_cvt_pk_bf16_f32 v21, v34, v36
	v_lshl_add_u64 v[40:41], v[38:39], 0, v[4:5]
	global_store_dwordx4 v[40:41], v[18:21], off nt
	v_or_b32_e32 v0, s12, v15
	v_lshlrev_b32_e32 v4, 12, v0
	v_cvt_pk_bf16_f32 v18, v25, v13
	v_cvt_pk_bf16_f32 v19, v27, v29
	v_cvt_pk_bf16_f32 v20, v31, v33
	v_cvt_pk_bf16_f32 v21, v35, v37
	ds_read2_b32 v[24:25], v14 offset0:49 offset1:57
	ds_read2_b32 v[26:27], v14 offset0:16 offset1:24
	ds_read2_b32 v[28:29], v14 offset0:82 offset1:90
	ds_read2_b32 v[30:31], v14 offset0:115 offset1:123
	ds_read2_b32 v[32:33], v14 offset0:148 offset1:156
	ds_read2_b32 v[34:35], v14 offset0:181 offset1:189
	ds_read2_b32 v[36:37], v14 offset0:214 offset1:222
	ds_read2_b32 v[40:41], v14 offset0:247 offset1:255
	v_or_b32_e32 v0, s12, v16
	v_lshl_add_u64 v[12:13], v[38:39], 0, v[4:5]
	v_lshlrev_b32_e32 v4, 12, v0
	v_or_b32_e32 v0, s12, v17
	global_store_dwordx4 v[12:13], v[18:21], off nt
	v_lshl_add_u64 v[12:13], v[38:39], 0, v[4:5]
	v_lshlrev_b32_e32 v4, 12, v0
	s_waitcnt lgkmcnt(6)
	v_cvt_pk_bf16_f32 v18, v26, v24
	s_waitcnt lgkmcnt(4)
	v_cvt_pk_bf16_f32 v19, v28, v30
	s_waitcnt lgkmcnt(2)
	v_cvt_pk_bf16_f32 v20, v32, v34
	s_waitcnt lgkmcnt(0)
	v_cvt_pk_bf16_f32 v21, v36, v40
	global_store_dwordx4 v[12:13], v[18:21], off nt
	v_lshl_add_u64 v[12:13], v[38:39], 0, v[4:5]
	s_nop 0
	v_cvt_pk_bf16_f32 v18, v27, v25
	v_cvt_pk_bf16_f32 v19, v29, v31
	v_cvt_pk_bf16_f32 v20, v33, v35
	v_cvt_pk_bf16_f32 v21, v37, v41
	global_store_dwordx4 v[12:13], v[18:21], off nt
	s_waitcnt lgkmcnt(0)

; #define GAS __attribute__((address_space(1)))
; #define LAS __attribute__((address_space(3)))
; #define LDS_WAIT() asm volatile("s_waitcnt lgkmcnt(0)" ::: "memory")
; __device__ __forceinline__ unsigned pk2(float lo, float hi) { return pg8::pkc(lo, hi); }
;     if (ldt == 0) ldt = K;
;     const int nblk = N / 32, kb = item / nblk, nb = item % nblk, k0 = 64 * kb, n0 = 32 * nb;
; #pragma unroll 8
;     for (int i = 0; i < 32; ++i) { const int kk = 2 * i + (lane >> 5); scr[kk * 33 + (lane & 31)] = W[(size_t)(k0 + kk) * N + n0 + (lane & 31)]; }
;     LDS_WAIT(); asm volatile("" ::: "memory");
;     const int c = lane & 7;
; #pragma unroll
;     for (int j = 0; j < 4; ++j) { const int n = (lane >> 3) + 8 * j; const LAS float* s = scr + (8 * c) * 33 + n;
;         v4u o; o.x = pk2(s[0 * 33], s[1 * 33]); o.y = pk2(s[2 * 33], s[3 * 33]); o.z = pk2(s[4 * 33], s[5 * 33]); o.w = pk2(s[6 * 33], s[7 * 33]);
;         *(GAS v4u*)(WT + (size_t)(n0 + n) * ldt + k0 + 8 * c) = o; }
;     LDS_WAIT(); asm volatile("" ::: "memory");
.LBB0_30:
	s_lshl_b32 s37, s35, 1
	s_lshl_b32 s38, s6, 1
	v_or_b32_e32 v0, s37, v1
	v_or_b32_e32 v4, s38, v2
	s_add_i32 s39, s37, 4
	s_add_i32 s42, s38, 4
	s_add_i32 s43, s37, 8
	s_add_i32 s44, s38, 8
	s_add_i32 s45, s37, 12
	s_add_i32 s46, s38, 12
	s_add_i32 s47, s37, 16
	s_add_i32 s48, s38, 16
	s_add_i32 s49, s37, 20
	s_add_i32 s50, s38, 20
	s_add_i32 s51, s37, 24
	s_add_i32 s52, s38, 24
	s_add_i32 s37, s37, 28
	s_add_i32 s38, s38, 28
	v_add_u32_e32 v9, s34, v0
	v_add_u32_e32 v11, s33, v4
	v_or_b32_e32 v23, s39, v1
	v_or_b32_e32 v52, s42, v2
	v_or_b32_e32 v53, s43, v1
	v_or_b32_e32 v54, s44, v2
	v_or_b32_e32 v55, s45, v1
	v_or_b32_e32 v56, s46, v2
	v_or_b32_e32 v57, s47, v1
	v_or_b32_e32 v58, s48, v2
	v_or_b32_e32 v59, s49, v1
	v_or_b32_e32 v60, s50, v2
	v_or_b32_e32 v61, s51, v1
	v_or_b32_e32 v62, s52, v2
	v_or_b32_e32 v63, s37, v1
	v_or_b32_e32 v64, s38, v2
	v_mad_u64_u32 v[18:19], s[38:39], v11, s30, v[12:13]
	v_mad_u64_u32 v[20:21], s[38:39], v9, s30, v[12:13]
	v_add_u32_e32 v9, s34, v23
	v_add_u32_e32 v11, s33, v52
	v_add_u32_e32 v30, s34, v53
	v_add_u32_e32 v28, s33, v54
	v_add_u32_e32 v34, s34, v55
	v_add_u32_e32 v32, s33, v56
	v_add_u32_e32 v38, s34, v57
	v_add_u32_e32 v36, s33, v58
	v_add_u32_e32 v42, s34, v59
	v_add_u32_e32 v40, s33, v60
	v_add_u32_e32 v46, s34, v61
	v_add_u32_e32 v44, s33, v62
	v_add_u32_e32 v50, s34, v63
	v_add_u32_e32 v48, s33, v64
	v_mad_u64_u32 v[24:25], s[38:39], v11, s30, v[12:13]
	v_mad_u64_u32 v[26:27], s[38:39], v9, s30, v[12:13]
	v_mad_u64_u32 v[28:29], s[38:39], v28, s30, v[12:13]
	v_mad_u64_u32 v[30:31], s[38:39], v30, s30, v[12:13]
	v_mad_u64_u32 v[32:33], s[38:39], v32, s30, v[12:13]
	v_mad_u64_u32 v[34:35], s[38:39], v34, s30, v[12:13]
	v_mad_u64_u32 v[36:37], s[38:39], v36, s30, v[12:13]
	v_mad_u64_u32 v[38:39], s[38:39], v38, s30, v[12:13]
	v_mad_u64_u32 v[40:41], s[38:39], v40, s30, v[12:13]
	v_mad_u64_u32 v[42:43], s[38:39], v42, s30, v[12:13]
	v_mad_u64_u32 v[44:45], s[38:39], v44, s30, v[12:13]
	v_mad_u64_u32 v[46:47], s[38:39], v46, s30, v[12:13]
	v_mad_u64_u32 v[48:49], s[38:39], v48, s30, v[12:13]
	v_mad_u64_u32 v[50:51], s[38:39], v50, s30, v[12:13]
	global_load_dword v9, v[18:19], off nt
	global_load_dword v11, v[20:21], off nt
	global_load_dword v65, v[24:25], off nt
	global_load_dword v66, v[26:27], off nt
	global_load_dword v67, v[28:29], off nt
	global_load_dword v68, v[30:31], off nt
	global_load_dword v69, v[32:33], off nt
	global_load_dword v70, v[34:35], off nt
	global_load_dword v71, v[36:37], off nt
	global_load_dword v72, v[38:39], off nt
	global_load_dword v73, v[40:41], off nt
	global_load_dword v74, v[42:43], off nt
	global_load_dword v75, v[44:45], off nt
	global_load_dword v76, v[46:47], off nt
	global_load_dword v77, v[48:49], off nt
	global_load_dword v78, v[50:51], off nt
	s_add_i32 s6, s6, 16
	s_add_i32 s35, s35, 16
	s_add_i32 s36, s36, -16
	v_mad_u64_u32 v[18:19], s[38:39], v4, s29, v[6:7]
	s_cmp_lg_u32 s36, 0
	v_mad_u64_u32 v[20:21], s[38:39], v0, s29, v[6:7]
	v_mad_u64_u32 v[24:25], s[38:39], v52, s29, v[6:7]
	v_mad_u64_u32 v[26:27], s[38:39], v23, s29, v[6:7]
	v_mad_u64_u32 v[28:29], s[38:39], v54, s29, v[6:7]
	v_mad_u64_u32 v[30:31], s[38:39], v53, s29, v[6:7]
	v_mad_u64_u32 v[32:33], s[38:39], v56, s29, v[6:7]
	v_mad_u64_u32 v[34:35], s[38:39], v55, s29, v[6:7]
	v_mad_u64_u32 v[36:37], s[38:39], v58, s29, v[6:7]
	v_mad_u64_u32 v[38:39], s[38:39], v57, s29, v[6:7]
	v_mad_u64_u32 v[40:41], s[38:39], v60, s29, v[6:7]
	v_mad_u64_u32 v[42:43], s[38:39], v59, s29, v[6:7]
	v_mad_u64_u32 v[44:45], s[38:39], v62, s29, v[6:7]
	v_mad_u64_u32 v[46:47], s[38:39], v61, s29, v[6:7]
	v_mad_u64_u32 v[48:49], s[38:39], v64, s29, v[6:7]
	v_mad_u64_u32 v[50:51], s[38:39], v63, s29, v[6:7]
	s_waitcnt vmcnt(15)
	ds_write_b32 v18, v9
	s_waitcnt vmcnt(14)
	ds_write_b32 v20, v11
	s_waitcnt vmcnt(13)
	ds_write_b32 v24, v65
	s_waitcnt vmcnt(12)
	ds_write_b32 v26, v66
	s_waitcnt vmcnt(11)
	ds_write_b32 v28, v67
	s_waitcnt vmcnt(10)
	ds_write_b32 v30, v68
	s_waitcnt vmcnt(9)
	ds_write_b32 v32, v69
	s_waitcnt vmcnt(8)
	ds_write_b32 v34, v70
	s_waitcnt vmcnt(7)
	ds_write_b32 v36, v71
	s_waitcnt vmcnt(6)
	ds_write_b32 v38, v72
	s_waitcnt vmcnt(5)
	ds_write_b32 v40, v73
	s_waitcnt vmcnt(4)
	ds_write_b32 v42, v74
	s_waitcnt vmcnt(3)
	ds_write_b32 v44, v75
	s_waitcnt vmcnt(2)
	ds_write_b32 v46, v76
	s_waitcnt vmcnt(1)
	ds_write_b32 v48, v77
	s_waitcnt vmcnt(0)
	ds_write_b32 v50, v78
	s_cbranch_scc1 .LBB0_30
	s_and_b64 s[10:11], s[10:11], exec
	s_cselect_b32 s6, 0x1900000, 0
	s_waitcnt lgkmcnt(0)
	s_add_u32 s6, s4, s6
	s_addc_u32 s11, s5, 0
	s_and_b32 s10, 0xffff, s12
	ds_read2_b32 v[12:13], v14 offset0:33 offset1:41
	ds_read2_b32 v[24:25], v14 offset1:8
	ds_read2_b32 v[26:27], v14 offset0:66 offset1:74
	ds_read2_b32 v[28:29], v14 offset0:99 offset1:107
	ds_read2_b32 v[30:31], v14 offset0:132 offset1:140
	ds_read2_b32 v[32:33], v14 offset0:165 offset1:173
	ds_read2_b32 v[34:35], v14 offset0:198 offset1:206
	ds_read2_b32 v[36:37], v14 offset0:231 offset1:239
	s_and_b32 s13, 0xffff, s13
	s_lshl_b32 s10, s10, 1
	s_add_u32 s10, s6, s10
	s_addc_u32 s11, s11, 0
	v_mov_b32_e32 v11, v5
	v_or_b32_e32 v0, s13, v3
	v_lshl_add_u64 v[38:39], s[10:11], 0, v[10:11]
	v_lshlrev_b32_e32 v4, 12, v0
	s_waitcnt lgkmcnt(6)
	v_cvt_pk_bf16_f32 v18, v24, v12
	s_waitcnt lgkmcnt(4)
	v_cvt_pk_bf16_f32 v19, v26, v28
	s_waitcnt lgkmcnt(2)
	v_cvt_pk_bf16_f32 v20, v30, v32
	s_waitcnt lgkmcnt(0)
	v_cvt_pk_bf16_f32 v21, v34, v36
	v_lshl_add_u64 v[40:41], v[38:39], 0, v[4:5]
	global_store_dwordx4 v[40:41], v[18:21], off nt
	v_or_b32_e32 v0, s13, v15
	v_lshlrev_b32_e32 v4, 12, v0
	v_cvt_pk_bf16_f32 v18, v25, v13
	v_cvt_pk_bf16_f32 v19, v27, v29
	v_cvt_pk_bf16_f32 v20, v31, v33
	v_cvt_pk_bf16_f32 v21, v35, v37
	ds_read2_b32 v[24:25], v14 offset0:49 offset1:57
	ds_read2_b32 v[26:27], v14 offset0:16 offset1:24
	ds_read2_b32 v[28:29], v14 offset0:82 offset1:90
	ds_read2_b32 v[30:31], v14 offset0:115 offset1:123
	ds_read2_b32 v[32:33], v14 offset0:148 offset1:156
	ds_read2_b32 v[34:35], v14 offset0:181 offset1:189
	ds_read2_b32 v[36:37], v14 offset0:214 offset1:222
	ds_read2_b32 v[40:41], v14 offset0:247 offset1:255
	v_or_b32_e32 v0, s13, v16
	v_lshl_add_u64 v[12:13], v[38:39], 0, v[4:5]
	v_lshlrev_b32_e32 v4, 12, v0
	v_or_b32_e32 v0, s13, v17
	global_store_dwordx4 v[12:13], v[18:21], off nt
	v_lshl_add_u64 v[12:13], v[38:39], 0, v[4:5]
	v_lshlrev_b32_e32 v4, 12, v0
	s_waitcnt lgkmcnt(6)
	v_cvt_pk_bf16_f32 v18, v26, v24
	s_waitcnt lgkmcnt(4)
	v_cvt_pk_bf16_f32 v19, v28, v30
	s_waitcnt lgkmcnt(2)
	v_cvt_pk_bf16_f32 v20, v32, v34
	s_waitcnt lgkmcnt(0)
	v_cvt_pk_bf16_f32 v21, v36, v40
	global_store_dwordx4 v[12:13], v[18:21], off nt
	v_lshl_add_u64 v[12:13], v[38:39], 0, v[4:5]
	s_nop 0
	v_cvt_pk_bf16_f32 v18, v27, v25
	v_cvt_pk_bf16_f32 v19, v29, v31
	v_cvt_pk_bf16_f32 v20, v33, v35
	v_cvt_pk_bf16_f32 v21, v37, v41
	global_store_dwordx4 v[12:13], v[18:21], off nt
	s_waitcnt lgkmcnt(0)

; #define LDS_WAIT() asm volatile("s_waitcnt lgkmcnt(0)" ::: "memory")
;     if (ldt == 0) ldt = K;
;     const int nblk = N / 32, kb = item / nblk, nb = item % nblk, k0 = 64 * kb, n0 = 32 * nb;
; #pragma unroll 8
;     for (int i = 0; i < 32; ++i) { const int kk = 2 * i + (lane >> 5); scr[kk * 33 + (lane & 31)] = W[(size_t)(k0 + kk) * N + n0 + (lane & 31)]; }
;     LDS_WAIT(); asm volatile("" ::: "memory");
.LBB0_35:
	s_lshl_b32 s35, s13, 1
	s_lshl_b32 s36, s33, 1
	v_or_b32_e32 v9, s36, v2
	s_add_i32 s37, s35, 4
	s_add_i32 s38, s36, 4
	s_add_i32 s42, s36, 8
	v_add_u32_e32 v4, s10, v9
	v_or_b32_e32 v11, s37, v1
	v_or_b32_e32 v23, s38, v2
	v_mov_b32_e32 v21, v5
	v_or_b32_e32 v0, s35, v1
	s_add_i32 s44, s36, 12
	v_or_b32_e32 v43, s42, v2
	v_lshlrev_b64 v[36:37], 13, v[4:5]
	v_add_u32_e32 v20, s12, v11
	v_add_u32_e32 v4, s10, v23
	v_mov_b32_e32 v19, v5
	s_add_i32 s39, s35, 8
	s_add_i32 s43, s35, 12
	s_add_i32 s46, s36, 16
	v_add_u32_e32 v18, s12, v0
	v_or_b32_e32 v45, s44, v2
	v_lshlrev_b64 v[20:21], 13, v[20:21]
	v_lshlrev_b64 v[38:39], 13, v[4:5]
	v_add_u32_e32 v4, s10, v43
	s_add_i32 s48, s36, 20
	v_or_b32_e32 v42, s39, v1
	v_or_b32_e32 v44, s43, v1
	v_or_b32_e32 v47, s46, v2
	v_lshlrev_b64 v[18:19], 13, v[18:19]
	v_lshl_add_u64 v[36:37], v[12:13], 0, v[36:37]
	v_lshl_add_u64 v[20:21], v[12:13], 0, v[20:21]
	v_lshlrev_b64 v[40:41], 13, v[4:5]
	v_add_u32_e32 v4, s10, v45
	v_mov_b32_e32 v25, v5
	v_mov_b32_e32 v27, v5
	s_add_i32 s45, s35, 16
	s_add_i32 s47, s35, 20
	s_add_i32 s50, s36, 24
	v_or_b32_e32 v49, s48, v2
	v_add_u32_e32 v24, s12, v42
	v_add_u32_e32 v26, s12, v44
	v_lshl_add_u64 v[18:19], v[12:13], 0, v[18:19]
	v_lshl_add_u64 v[38:39], v[12:13], 0, v[38:39]
	global_load_dword v54, v[36:37], off nt
	global_load_dword v55, v[18:19], off nt
	global_load_dword v56, v[38:39], off nt
	global_load_dword v57, v[20:21], off nt
	v_lshlrev_b64 v[20:21], 13, v[4:5]
	v_add_u32_e32 v4, s10, v47
	s_add_i32 s49, s35, 24
	s_add_i32 s35, s35, 28
	s_add_i32 s36, s36, 28
	v_or_b32_e32 v46, s45, v1
	v_or_b32_e32 v48, s47, v1
	v_or_b32_e32 v51, s50, v2
	v_lshlrev_b64 v[24:25], 13, v[24:25]
	v_lshlrev_b64 v[26:27], 13, v[26:27]
	v_lshl_add_u64 v[18:19], v[12:13], 0, v[40:41]
	v_lshl_add_u64 v[20:21], v[12:13], 0, v[20:21]
	v_lshlrev_b64 v[36:37], 13, v[4:5]
	v_add_u32_e32 v4, s10, v49
	v_mov_b32_e32 v29, v5
	v_mov_b32_e32 v31, v5
	v_or_b32_e32 v50, s49, v1
	v_or_b32_e32 v52, s35, v1
	v_or_b32_e32 v53, s36, v2
	v_add_u32_e32 v28, s12, v46
	v_add_u32_e32 v30, s12, v48
	v_lshl_add_u64 v[24:25], v[12:13], 0, v[24:25]
	v_lshl_add_u64 v[26:27], v[12:13], 0, v[26:27]
	global_load_dword v58, v[18:19], off nt
	global_load_dword v59, v[24:25], off nt
	global_load_dword v60, v[20:21], off nt
	global_load_dword v61, v[26:27], off nt
	v_lshlrev_b64 v[20:21], 13, v[4:5]
	v_add_u32_e32 v4, s10, v51
	v_mov_b32_e32 v33, v5
	v_mov_b32_e32 v35, v5
	v_add_u32_e32 v32, s12, v50
	v_add_u32_e32 v34, s12, v52
	v_lshlrev_b64 v[28:29], 13, v[28:29]
	v_lshlrev_b64 v[30:31], 13, v[30:31]
	v_lshl_add_u64 v[18:19], v[12:13], 0, v[36:37]
	v_lshl_add_u64 v[20:21], v[12:13], 0, v[20:21]
	v_lshlrev_b64 v[24:25], 13, v[4:5]
	v_add_u32_e32 v4, s10, v53
	v_lshlrev_b64 v[32:33], 13, v[32:33]
	v_lshlrev_b64 v[34:35], 13, v[34:35]
	v_lshl_add_u64 v[28:29], v[12:13], 0, v[28:29]
	v_lshl_add_u64 v[30:31], v[12:13], 0, v[30:31]
	global_load_dword v62, v[18:19], off nt
	global_load_dword v63, v[28:29], off nt
	global_load_dword v64, v[20:21], off nt
	global_load_dword v65, v[30:31], off nt
	v_lshl_add_u64 v[18:19], v[12:13], 0, v[24:25]
	v_lshlrev_b64 v[20:21], 13, v[4:5]
	v_lshl_add_u64 v[32:33], v[12:13], 0, v[32:33]
	v_lshl_add_u64 v[34:35], v[12:13], 0, v[34:35]
	v_lshl_add_u64 v[20:21], v[12:13], 0, v[20:21]
	global_load_dword v4, v[18:19], off nt
	global_load_dword v66, v[32:33], off nt
	global_load_dword v67, v[20:21], off nt
	global_load_dword v68, v[34:35], off nt
	s_add_i32 s33, s33, 16
	s_add_i32 s13, s13, 16
	s_add_i32 s34, s34, -16
	v_mad_u64_u32 v[18:19], s[36:37], v9, s29, v[6:7]
	s_cmp_lg_u32 s34, 0
	v_mad_u64_u32 v[20:21], s[36:37], v0, s29, v[6:7]
	v_mad_u64_u32 v[24:25], s[36:37], v23, s29, v[6:7]
	v_mad_u64_u32 v[26:27], s[36:37], v11, s29, v[6:7]
	v_mad_u64_u32 v[28:29], s[36:37], v43, s29, v[6:7]
	v_mad_u64_u32 v[30:31], s[36:37], v42, s29, v[6:7]
	v_mad_u64_u32 v[32:33], s[36:37], v45, s29, v[6:7]
	v_mad_u64_u32 v[34:35], s[36:37], v44, s29, v[6:7]
	v_mad_u64_u32 v[36:37], s[36:37], v47, s29, v[6:7]
	v_mad_u64_u32 v[38:39], s[36:37], v46, s29, v[6:7]
	v_mad_u64_u32 v[40:41], s[36:37], v49, s29, v[6:7]
	v_mad_u64_u32 v[42:43], s[36:37], v48, s29, v[6:7]
	v_mad_u64_u32 v[44:45], s[36:37], v51, s29, v[6:7]
	v_mad_u64_u32 v[46:47], s[36:37], v50, s29, v[6:7]
	v_mad_u64_u32 v[48:49], s[36:37], v53, s29, v[6:7]
	v_mad_u64_u32 v[50:51], s[36:37], v52, s29, v[6:7]
	s_waitcnt vmcnt(15)
	ds_write_b32 v18, v54
	s_waitcnt vmcnt(14)
	ds_write_b32 v20, v55
	s_waitcnt vmcnt(13)
	ds_write_b32 v24, v56
	s_waitcnt vmcnt(12)
	ds_write_b32 v26, v57
	s_waitcnt vmcnt(11)
	ds_write_b32 v28, v58
	s_waitcnt vmcnt(10)
	ds_write_b32 v30, v59
	s_waitcnt vmcnt(9)
	ds_write_b32 v32, v60
	s_waitcnt vmcnt(8)
	ds_write_b32 v34, v61
	s_waitcnt vmcnt(7)
	ds_write_b32 v36, v62
	s_waitcnt vmcnt(6)
	ds_write_b32 v38, v63
	s_waitcnt vmcnt(5)
	ds_write_b32 v40, v64
	s_waitcnt vmcnt(4)
	ds_write_b32 v42, v65
	s_waitcnt vmcnt(3)
	ds_write_b32 v44, v4
	s_waitcnt vmcnt(2)
	ds_write_b32 v46, v66
	s_waitcnt vmcnt(1)
	ds_write_b32 v48, v67
	s_waitcnt vmcnt(0)
	ds_write_b32 v50, v68
	s_cbranch_scc1 .LBB0_35
; #define GAS __attribute__((address_space(1)))
; #define LAS __attribute__((address_space(3)))
; #define LDS_WAIT() asm volatile("s_waitcnt lgkmcnt(0)" ::: "memory")
; __device__ __forceinline__ unsigned pk2(float lo, float hi) { return pg8::pkc(lo, hi); }
;     ...
;     const int c = lane & 7;
; #pragma unroll
;     for (int j = 0; j < 4; ++j) { const int n = (lane >> 3) + 8 * j; const LAS float* s = scr + (8 * c) * 33 + n;
;         v4u o; o.x = pk2(s[0 * 33], s[1 * 33]); o.y = pk2(s[2 * 33], s[3 * 33]); o.z = pk2(s[4 * 33], s[5 * 33]); o.w = pk2(s[6 * 33], s[7 * 33]);
;         *(GAS v4u*)(WT + (size_t)(n0 + n) * ldt + k0 + 8 * c) = o; }
;     LDS_WAIT(); asm volatile("" ::: "memory");
	s_mul_i32 s6, s6, 0x1680000
	s_waitcnt lgkmcnt(0)
	s_add_u32 s6, s27, s6
	s_addc_u32 s12, s28, 0
	s_and_b32 s10, 0xffff, s10
	ds_read2_b32 v[12:13], v14 offset0:33 offset1:41
	ds_read2_b32 v[24:25], v14 offset1:8
	ds_read2_b32 v[26:27], v14 offset0:66 offset1:74
	ds_read2_b32 v[28:29], v14 offset0:99 offset1:107
	ds_read2_b32 v[30:31], v14 offset0:132 offset1:140
	ds_read2_b32 v[32:33], v14 offset0:165 offset1:173
	ds_read2_b32 v[34:35], v14 offset0:198 offset1:206
	ds_read2_b32 v[36:37], v14 offset0:231 offset1:239
	s_and_b32 s13, 0xffff, s11
	s_lshl_b32 s10, s10, 1
	s_add_u32 s10, s6, s10
	s_addc_u32 s11, s12, 0
	v_mov_b32_e32 v11, v5
	v_or_b32_e32 v0, s13, v3
	v_lshl_add_u64 v[38:39], s[10:11], 0, v[10:11]
	v_mul_u32_u24_e32 v4, 0x2d00, v0
	s_waitcnt lgkmcnt(6)
	v_cvt_pk_bf16_f32 v18, v24, v12
	s_waitcnt lgkmcnt(4)
	v_cvt_pk_bf16_f32 v19, v26, v28
	s_waitcnt lgkmcnt(2)
	v_cvt_pk_bf16_f32 v20, v30, v32
	s_waitcnt lgkmcnt(0)
	v_cvt_pk_bf16_f32 v21, v34, v36
	v_lshl_add_u64 v[40:41], v[38:39], 0, v[4:5]
	global_store_dwordx4 v[40:41], v[18:21], off nt
	v_or_b32_e32 v0, s13, v15
	v_mul_u32_u24_e32 v4, 0x2d00, v0
	v_cvt_pk_bf16_f32 v18, v25, v13
	v_cvt_pk_bf16_f32 v19, v27, v29
	v_cvt_pk_bf16_f32 v20, v31, v33
	v_cvt_pk_bf16_f32 v21, v35, v37
	ds_read2_b32 v[24:25], v14 offset0:16 offset1:24
	ds_read2_b32 v[26:27], v14 offset0:49 offset1:57
	ds_read2_b32 v[28:29], v14 offset0:82 offset1:90
	ds_read2_b32 v[30:31], v14 offset0:115 offset1:123
	ds_read2_b32 v[32:33], v14 offset0:148 offset1:156
	ds_read2_b32 v[34:35], v14 offset0:181 offset1:189
	ds_read2_b32 v[36:37], v14 offset0:214 offset1:222
	ds_read2_b32 v[40:41], v14 offset0:247 offset1:255
	v_or_b32_e32 v0, s13, v16
	v_lshl_add_u64 v[12:13], v[38:39], 0, v[4:5]
	v_mul_u32_u24_e32 v4, 0x2d00, v0
	v_or_b32_e32 v0, s13, v17
	global_store_dwordx4 v[12:13], v[18:21], off nt
	v_lshl_add_u64 v[12:13], v[38:39], 0, v[4:5]
	v_mul_u32_u24_e32 v4, 0x2d00, v0
	s_waitcnt lgkmcnt(6)
	v_cvt_pk_bf16_f32 v18, v24, v26
	s_waitcnt lgkmcnt(4)
	v_cvt_pk_bf16_f32 v19, v28, v30
	s_waitcnt lgkmcnt(2)
	v_cvt_pk_bf16_f32 v20, v32, v34
	s_waitcnt lgkmcnt(0)
	v_cvt_pk_bf16_f32 v21, v36, v40
	global_store_dwordx4 v[12:13], v[18:21], off nt
	v_lshl_add_u64 v[12:13], v[38:39], 0, v[4:5]
	s_nop 0
	v_cvt_pk_bf16_f32 v18, v25, v27
	v_cvt_pk_bf16_f32 v19, v29, v31
	v_cvt_pk_bf16_f32 v20, v33, v35
	v_cvt_pk_bf16_f32 v21, v37, v41
	global_store_dwordx4 v[12:13], v[18:21], off nt
	s_waitcnt lgkmcnt(0)

; #define LAS __attribute__((address_space(3)))
; #define LDS_WAIT() asm volatile("s_waitcnt lgkmcnt(0)" ::: "memory")
; __device__ __forceinline__ void p0_transpose_item_up(const float* W, bf16* WT, LAS float* scr, int item, int lane) {
;     constexpr int K = D, N = DUP;
;     const int nblk = N / 32, kb = item / nblk, nb = item % nblk, k0 = 64 * kb, n0 = 32 * nb;
;     const int isg = n0 >= DFF, c0 = isg ? n0 - DFF : n0, d0 = 256 * (c0 >> 7) + (isg ? 128 : 0) + (c0 & 127);
; #pragma unroll 8
;     for (int i = 0; i < 32; ++i) { const int kk = 2 * i + (lane >> 5); scr[kk * 33 + (lane & 31)] = W[(size_t)(k0 + kk) * N + n0 + (lane & 31)]; }
;     LDS_WAIT(); asm volatile("" ::: "memory");
.LBB0_39:
	s_lshl_b32 s36, s33, 1
	s_lshl_b32 s37, s34, 1
	v_or_b32_e32 v0, s36, v1
	v_or_b32_e32 v4, s37, v2
	s_add_i32 s38, s36, 4
	s_add_i32 s39, s37, 4
	s_add_i32 s42, s36, 8
	s_add_i32 s43, s37, 8
	s_add_i32 s44, s36, 12
	s_add_i32 s45, s37, 12
	s_add_i32 s46, s36, 16
	s_add_i32 s47, s37, 16
	s_add_i32 s48, s36, 20
	s_add_i32 s49, s37, 20
	s_add_i32 s50, s36, 24
	s_add_i32 s51, s37, 24
	s_add_i32 s36, s36, 28
	s_add_i32 s37, s37, 28
	v_add_u32_e32 v9, s13, v0
	v_add_u32_e32 v11, s10, v4
	v_or_b32_e32 v23, s38, v1
	v_or_b32_e32 v52, s39, v2
	v_or_b32_e32 v53, s42, v1
	v_or_b32_e32 v54, s43, v2
	v_or_b32_e32 v55, s44, v1
	v_or_b32_e32 v56, s45, v2
	v_or_b32_e32 v57, s46, v1
	v_or_b32_e32 v58, s47, v2
	v_or_b32_e32 v59, s48, v1
	v_or_b32_e32 v60, s49, v2
	v_or_b32_e32 v61, s50, v1
	v_or_b32_e32 v62, s51, v2
	v_or_b32_e32 v63, s36, v1
	v_or_b32_e32 v64, s37, v2
	v_mad_i64_i32 v[18:19], s[36:37], v11, s31, v[12:13]
	v_mad_i64_i32 v[20:21], s[36:37], v9, s31, v[12:13]
	v_add_u32_e32 v9, s13, v23
	v_add_u32_e32 v11, s10, v52
	v_add_u32_e32 v30, s13, v53
	v_add_u32_e32 v28, s10, v54
	v_add_u32_e32 v34, s13, v55
	v_add_u32_e32 v32, s10, v56
	v_add_u32_e32 v38, s13, v57
	v_add_u32_e32 v36, s10, v58
	v_add_u32_e32 v42, s13, v59
	v_add_u32_e32 v40, s10, v60
	v_add_u32_e32 v46, s13, v61
	v_add_u32_e32 v44, s10, v62
	v_add_u32_e32 v50, s13, v63
	v_add_u32_e32 v48, s10, v64
	v_mad_i64_i32 v[24:25], s[36:37], v11, s31, v[12:13]
	v_mad_i64_i32 v[26:27], s[36:37], v9, s31, v[12:13]
	v_mad_i64_i32 v[28:29], s[36:37], v28, s31, v[12:13]
	v_mad_i64_i32 v[30:31], s[36:37], v30, s31, v[12:13]
	v_mad_i64_i32 v[32:33], s[36:37], v32, s31, v[12:13]
	v_mad_i64_i32 v[34:35], s[36:37], v34, s31, v[12:13]
	v_mad_i64_i32 v[36:37], s[36:37], v36, s31, v[12:13]
	v_mad_i64_i32 v[38:39], s[36:37], v38, s31, v[12:13]
	v_mad_i64_i32 v[40:41], s[36:37], v40, s31, v[12:13]
	v_mad_i64_i32 v[42:43], s[36:37], v42, s31, v[12:13]
	v_mad_i64_i32 v[44:45], s[36:37], v44, s31, v[12:13]
	v_mad_i64_i32 v[46:47], s[36:37], v46, s31, v[12:13]
	v_mad_i64_i32 v[48:49], s[36:37], v48, s31, v[12:13]
	v_mad_i64_i32 v[50:51], s[36:37], v50, s31, v[12:13]
	global_load_dword v9, v[18:19], off nt
	global_load_dword v11, v[20:21], off nt
	global_load_dword v65, v[24:25], off nt
	global_load_dword v66, v[26:27], off nt
	global_load_dword v67, v[28:29], off nt
	global_load_dword v68, v[30:31], off nt
	global_load_dword v69, v[32:33], off nt
	global_load_dword v70, v[34:35], off nt
	global_load_dword v71, v[36:37], off nt
	global_load_dword v72, v[38:39], off nt
	global_load_dword v73, v[40:41], off nt
	global_load_dword v74, v[42:43], off nt
	global_load_dword v75, v[44:45], off nt
	global_load_dword v76, v[46:47], off nt
	global_load_dword v77, v[48:49], off nt
	global_load_dword v78, v[50:51], off nt
	s_add_i32 s34, s34, 16
	s_add_i32 s33, s33, 16
	s_add_i32 s35, s35, -16
	v_mad_u64_u32 v[18:19], s[36:37], v4, s29, v[6:7]
	s_cmp_lg_u32 s35, 0
	v_mad_u64_u32 v[20:21], s[36:37], v0, s29, v[6:7]
	v_mad_u64_u32 v[24:25], s[36:37], v52, s29, v[6:7]
	v_mad_u64_u32 v[26:27], s[36:37], v23, s29, v[6:7]
	v_mad_u64_u32 v[28:29], s[36:37], v54, s29, v[6:7]
	v_mad_u64_u32 v[30:31], s[36:37], v53, s29, v[6:7]
	v_mad_u64_u32 v[32:33], s[36:37], v56, s29, v[6:7]
	v_mad_u64_u32 v[34:35], s[36:37], v55, s29, v[6:7]
	v_mad_u64_u32 v[36:37], s[36:37], v58, s29, v[6:7]
	v_mad_u64_u32 v[38:39], s[36:37], v57, s29, v[6:7]
	v_mad_u64_u32 v[40:41], s[36:37], v60, s29, v[6:7]
	v_mad_u64_u32 v[42:43], s[36:37], v59, s29, v[6:7]
	v_mad_u64_u32 v[44:45], s[36:37], v62, s29, v[6:7]
	v_mad_u64_u32 v[46:47], s[36:37], v61, s29, v[6:7]
	v_mad_u64_u32 v[48:49], s[36:37], v64, s29, v[6:7]
	v_mad_u64_u32 v[50:51], s[36:37], v63, s29, v[6:7]
	s_waitcnt vmcnt(15)
	ds_write_b32 v18, v9
	s_waitcnt vmcnt(14)
	ds_write_b32 v20, v11
	s_waitcnt vmcnt(13)
	ds_write_b32 v24, v65
	s_waitcnt vmcnt(12)
	ds_write_b32 v26, v66
	s_waitcnt vmcnt(11)
	ds_write_b32 v28, v67
	s_waitcnt vmcnt(10)
	ds_write_b32 v30, v68
	s_waitcnt vmcnt(9)
	ds_write_b32 v32, v69
	s_waitcnt vmcnt(8)
	ds_write_b32 v34, v70
	s_waitcnt vmcnt(7)
	ds_write_b32 v36, v71
	s_waitcnt vmcnt(6)
	ds_write_b32 v38, v72
	s_waitcnt vmcnt(5)
	ds_write_b32 v40, v73
	s_waitcnt vmcnt(4)
	ds_write_b32 v42, v74
	s_waitcnt vmcnt(3)
	ds_write_b32 v44, v75
	s_waitcnt vmcnt(2)
	ds_write_b32 v46, v76
	s_waitcnt vmcnt(1)
	ds_write_b32 v48, v77
	s_waitcnt vmcnt(0)
	ds_write_b32 v50, v78
	s_cbranch_scc1 .LBB0_39
; #define GAS __attribute__((address_space(1)))
; #define LAS __attribute__((address_space(3)))
; #define LDS_WAIT() asm volatile("s_waitcnt lgkmcnt(0)" ::: "memory")
; __device__ __forceinline__ unsigned pk2(float lo, float hi) { return pg8::pkc(lo, hi); }
; __device__ __forceinline__ void p0_transpose_item_up(const float* W, bf16* WT, LAS float* scr, int item, int lane) {
;     ...
;     const int nblk = N / 32, kb = item / nblk, nb = item % nblk, k0 = 64 * kb, n0 = 32 * nb;
;     const int isg = n0 >= DFF, c0 = isg ? n0 - DFF : n0, d0 = 256 * (c0 >> 7) + (isg ? 128 : 0) + (c0 & 127);
; #pragma unroll 8
;     for (int i = 0; i < 32; ++i) { const int kk = 2 * i + (lane >> 5); scr[kk * 33 + (lane & 31)] = W[(size_t)(k0 + kk) * N + n0 + (lane & 31)]; }
;     LDS_WAIT(); asm volatile("" ::: "memory");
;     const int c = lane & 7;
; #pragma unroll
;     for (int j = 0; j < 4; ++j) { const int n = (lane >> 3) + 8 * j; const LAS float* s = scr + (8 * c) * 33 + n;
;         v4u o; o.x = pk2(s[0 * 33], s[1 * 33]); o.y = pk2(s[2 * 33], s[3 * 33]); o.z = pk2(s[4 * 33], s[5 * 33]); o.w = pk2(s[6 * 33], s[7 * 33]);
;         *(GAS v4u*)(WT + (size_t)(d0 + n) * K + k0 + 8 * c) = o; }
;     LDS_WAIT(); asm volatile("" ::: "memory");
	s_mul_hi_i32 s13, s6, 0x2c00000
	s_mul_i32 s6, s6, 0x2c00000
	s_add_u32 s6, s25, s6
	s_addc_u32 s13, s26, s13
	s_add_i32 s33, s12, 0xffffea00
	s_cmpk_gt_i32 s11, 0xaf
	s_cselect_b32 s11, s33, s12
	s_cselect_b32 s12, 0x80, 0
	s_and_b32 s33, s11, 0x60
	s_lshl_b32 s11, s11, 1
	s_waitcnt lgkmcnt(0)
	s_and_b32 s11, s11, 0xffffff00
	s_or_b32 s12, s33, s12
	s_or_b32 s12, s12, s11
	s_ashr_i32 s11, s10, 31
	ds_read2_b32 v[12:13], v14 offset0:33 offset1:41
	ds_read2_b32 v[24:25], v14 offset1:8
	ds_read2_b32 v[26:27], v14 offset0:66 offset1:74
	ds_read2_b32 v[28:29], v14 offset0:99 offset1:107
	ds_read2_b32 v[30:31], v14 offset0:132 offset1:140
	ds_read2_b32 v[32:33], v14 offset0:165 offset1:173
	ds_read2_b32 v[34:35], v14 offset0:198 offset1:206
	ds_read2_b32 v[36:37], v14 offset0:231 offset1:239
	s_lshl_b64 s[10:11], s[10:11], 1
	s_add_u32 s10, s6, s10
	v_or_b32_e32 v40, s12, v3
	s_addc_u32 s11, s13, s11
	v_mov_b32_e32 v11, v5
	v_ashrrev_i32_e32 v41, 31, v40
	v_lshl_add_u64 v[38:39], s[10:11], 0, v[10:11]
	v_lshlrev_b64 v[40:41], 12, v[40:41]
	s_waitcnt lgkmcnt(6)
	v_cvt_pk_bf16_f32 v18, v24, v12
	s_waitcnt lgkmcnt(4)
	v_cvt_pk_bf16_f32 v19, v26, v28
	s_waitcnt lgkmcnt(2)
	v_cvt_pk_bf16_f32 v20, v30, v32
	s_waitcnt lgkmcnt(0)
	v_cvt_pk_bf16_f32 v21, v34, v36
	v_lshl_add_u64 v[40:41], v[38:39], 0, v[40:41]
	v_or_b32_e32 v12, s12, v15
	global_store_dwordx4 v[40:41], v[18:21], off nt
	s_nop 1
	v_cvt_pk_bf16_f32 v18, v25, v13
	v_ashrrev_i32_e32 v13, 31, v12
	v_cvt_pk_bf16_f32 v19, v27, v29
	v_cvt_pk_bf16_f32 v20, v31, v33
	v_cvt_pk_bf16_f32 v21, v35, v37
	v_lshlrev_b64 v[12:13], 12, v[12:13]
	ds_read2_b32 v[24:25], v14 offset0:49 offset1:57
	ds_read2_b32 v[26:27], v14 offset0:16 offset1:24
	ds_read2_b32 v[28:29], v14 offset0:82 offset1:90
	ds_read2_b32 v[30:31], v14 offset0:115 offset1:123
	ds_read2_b32 v[32:33], v14 offset0:148 offset1:156
	ds_read2_b32 v[34:35], v14 offset0:181 offset1:189
	ds_read2_b32 v[36:37], v14 offset0:214 offset1:222
	ds_read2_b32 v[40:41], v14 offset0:247 offset1:255
	v_lshl_add_u64 v[12:13], v[38:39], 0, v[12:13]
	global_store_dwordx4 v[12:13], v[18:21], off nt
	v_or_b32_e32 v12, s12, v16
	v_ashrrev_i32_e32 v13, 31, v12
	v_lshlrev_b64 v[12:13], 12, v[12:13]
	s_waitcnt lgkmcnt(6)
	v_cvt_pk_bf16_f32 v18, v26, v24
	s_waitcnt lgkmcnt(4)
	v_cvt_pk_bf16_f32 v19, v28, v30
	s_waitcnt lgkmcnt(2)
	v_cvt_pk_bf16_f32 v20, v32, v34
	s_waitcnt lgkmcnt(0)
	v_cvt_pk_bf16_f32 v21, v36, v40
	v_lshl_add_u64 v[12:13], v[38:39], 0, v[12:13]
	global_store_dwordx4 v[12:13], v[18:21], off nt
	v_or_b32_e32 v12, s12, v17
	v_ashrrev_i32_e32 v13, 31, v12
	v_lshlrev_b64 v[12:13], 12, v[12:13]
	v_cvt_pk_bf16_f32 v18, v27, v25
	v_cvt_pk_bf16_f32 v19, v29, v31
	v_cvt_pk_bf16_f32 v20, v33, v35
	v_cvt_pk_bf16_f32 v21, v37, v41
	v_lshl_add_u64 v[12:13], v[38:39], 0, v[12:13]
	global_store_dwordx4 v[12:13], v[18:21], off nt
	s_waitcnt lgkmcnt(0)
	s_branch .LBB0_14

; __device__ __forceinline__ void ph_prologue(Frame& F) {
;     ...
;                 for (int kk = 0; kk < 256; kk += 8) {
;                     f32x4 wv[8];
; #pragma unroll
;                     for (int u = 0; u < 8; ++u) wv[u] = *(const f32x4*)(Wp + (size_t)(kk + u) * MODW);
; #pragma unroll
;                     for (int u = 0; u < 8; ++u)
; #pragma unroll
;                         for (int r = 0; r < 5; ++r) { const float s = S[r * D + k0 + kk + u];
; #pragma unroll
;                             for (int cc = 0; cc < 4; ++cc) acc[r][cc] = fmaf(s, wv[u][cc], acc[r][cc]); }
.LBB0_68:
	v_add_co_u32_e64 v32, s[4:5], s23, v30
	v_mov_b32_e32 v0, s13
	s_nop 0
	v_addc_co_u32_e64 v33, s[4:5], -1, v31, s[4:5]
	v_add_co_u32_e64 v62, s[4:5], s24, v30
	global_load_dwordx4 v[34:37], v[30:31], off nt
	s_nop 0
	v_addc_co_u32_e64 v63, s[4:5], -1, v31, s[4:5]
	v_add_co_u32_e64 v64, s[4:5], s25, v30
	s_add_i32 s12, s12, 8
	s_nop 0
	v_addc_co_u32_e64 v65, s[4:5], -1, v31, s[4:5]
	v_add_co_u32_e64 v66, s[4:5], s26, v30
	s_add_i32 s13, s13, 32
	s_nop 0
	v_addc_co_u32_e64 v67, s[4:5], -1, v31, s[4:5]
	v_add_co_u32_e64 v68, s[4:5], s27, v30
	s_cmpk_gt_u32 s12, 0xf7
	s_nop 0
	v_addc_co_u32_e64 v69, s[4:5], -1, v31, s[4:5]
	v_add_co_u32_e64 v70, s[4:5], s28, v30
	s_nop 1
	v_addc_co_u32_e64 v71, s[4:5], -1, v31, s[4:5]
	v_add_co_u32_e64 v72, s[4:5], s29, v30
	global_load_dwordx4 v[38:41], v[32:33], off nt
	global_load_dwordx4 v[42:45], v[62:63], off nt
	global_load_dwordx4 v[46:49], v[64:65], off nt
	global_load_dwordx4 v[50:53], v[66:67], off nt
	global_load_dwordx4 v[54:57], v[68:69], off nt
	global_load_dwordx4 v[58:61], v[70:71], off nt
	v_addc_co_u32_e64 v73, s[4:5], -1, v31, s[4:5]
	ds_read_b128 v[62:65], v0
	ds_read_b128 v[66:69], v0 offset:16
	global_load_dwordx4 v[70:73], v[72:73], off nt
	ds_read_b128 v[74:77], v0 offset:8192
	ds_read_b128 v[78:81], v0 offset:8208
	ds_read_b128 v[82:85], v0 offset:16384
	ds_read_b128 v[86:89], v0 offset:16400
	ds_read_b128 v[90:93], v0 offset:24576
	ds_read_b128 v[94:97], v0 offset:24592
	ds_read_b128 v[98:101], v0 offset:32768
	ds_read_b128 v[102:105], v0 offset:32784
	s_waitcnt lgkmcnt(7)
	v_mov_b32_e32 v32, v77
	v_mov_b32_e32 v24, v65
	s_waitcnt lgkmcnt(5)
	v_mov_b32_e32 v106, v85
	s_waitcnt lgkmcnt(3)
	v_mov_b32_e32 v108, v93
	s_waitcnt lgkmcnt(1)
	v_mov_b32_e32 v110, v101
	v_mov_b32_e32 v112, v69
	v_mov_b32_e32 v114, v81
	v_mov_b32_e32 v116, v89
	v_mov_b32_e32 v118, v97
	s_waitcnt lgkmcnt(0)
	v_mov_b32_e32 v120, v105
	v_lshl_add_u64 v[30:31], v[30:31], 0, s[6:7]
	s_waitcnt vmcnt(6)
	v_pk_fma_f32 v[18:19], v[62:63], v[38:39], v[18:19] op_sel_hi:[0,1,1]
	v_pk_fma_f32 v[20:21], v[62:63], v[40:41], v[20:21] op_sel_hi:[0,1,1]
	v_pk_fma_f32 v[14:15], v[74:75], v[38:39], v[14:15] op_sel_hi:[0,1,1]
	v_pk_fma_f32 v[16:17], v[74:75], v[40:41], v[16:17] op_sel_hi:[0,1,1]
	v_pk_fma_f32 v[10:11], v[82:83], v[38:39], v[10:11] op_sel_hi:[0,1,1]
	v_pk_fma_f32 v[12:13], v[82:83], v[40:41], v[12:13] op_sel_hi:[0,1,1]
	v_pk_fma_f32 v[6:7], v[90:91], v[38:39], v[6:7] op_sel_hi:[0,1,1]
	v_pk_fma_f32 v[8:9], v[90:91], v[40:41], v[8:9] op_sel_hi:[0,1,1]
	v_pk_fma_f32 v[2:3], v[98:99], v[38:39], v[2:3] op_sel_hi:[0,1,1]
	v_pk_fma_f32 v[4:5], v[98:99], v[40:41], v[4:5] op_sel_hi:[0,1,1]
	s_waitcnt vmcnt(5)
	v_pk_fma_f32 v[18:19], v[62:63], v[42:43], v[18:19] op_sel:[1,0,0]
	v_pk_fma_f32 v[20:21], v[62:63], v[44:45], v[20:21] op_sel:[1,0,0]
	v_pk_fma_f32 v[14:15], v[74:75], v[42:43], v[14:15] op_sel:[1,0,0]
	v_pk_fma_f32 v[16:17], v[74:75], v[44:45], v[16:17] op_sel:[1,0,0]
	v_pk_fma_f32 v[10:11], v[82:83], v[42:43], v[10:11] op_sel:[1,0,0]
	v_pk_fma_f32 v[12:13], v[82:83], v[44:45], v[12:13] op_sel:[1,0,0]
	v_pk_fma_f32 v[6:7], v[90:91], v[42:43], v[6:7] op_sel:[1,0,0]
	v_pk_fma_f32 v[8:9], v[90:91], v[44:45], v[8:9] op_sel:[1,0,0]
	v_pk_fma_f32 v[2:3], v[98:99], v[42:43], v[2:3] op_sel:[1,0,0]
	v_pk_fma_f32 v[4:5], v[98:99], v[44:45], v[4:5] op_sel:[1,0,0]
	s_waitcnt vmcnt(4)
	v_pk_fma_f32 v[18:19], v[64:65], v[46:47], v[18:19] op_sel_hi:[0,1,1]
	v_pk_fma_f32 v[20:21], v[64:65], v[48:49], v[20:21] op_sel_hi:[0,1,1]
	v_pk_fma_f32 v[14:15], v[76:77], v[46:47], v[14:15] op_sel_hi:[0,1,1]
	v_pk_fma_f32 v[16:17], v[76:77], v[48:49], v[16:17] op_sel_hi:[0,1,1]
	v_pk_fma_f32 v[10:11], v[84:85], v[46:47], v[10:11] op_sel_hi:[0,1,1]
	v_pk_fma_f32 v[12:13], v[84:85], v[48:49], v[12:13] op_sel_hi:[0,1,1]
	v_pk_fma_f32 v[6:7], v[92:93], v[46:47], v[6:7] op_sel_hi:[0,1,1]
	v_pk_fma_f32 v[8:9], v[92:93], v[48:49], v[8:9] op_sel_hi:[0,1,1]
	v_pk_fma_f32 v[2:3], v[100:101], v[46:47], v[2:3] op_sel_hi:[0,1,1]
	v_pk_fma_f32 v[4:5], v[100:101], v[48:49], v[4:5] op_sel_hi:[0,1,1]
	s_waitcnt vmcnt(3)
; __device__ __forceinline__ void ph_prologue(Frame& F) {
;     ...
;                     for (int u = 0; u < 8; ++u)
; #pragma unroll
;                         for (int r = 0; r < 5; ++r) { const float s = S[r * D + k0 + kk + u];
; #pragma unroll
;                             for (int cc = 0; cc < 4; ++cc) acc[r][cc] = fmaf(s, wv[u][cc], acc[r][cc]); }
;                 }
; #pragma unroll
;                 for (int r = 0; r < 5; ++r)
; #pragma unroll
;                     for (int cc = 0; cc < 4; ++cc) RED[(F.wave * 5 + r) * 256 + 4 * F.lane + cc] = acc[r][cc];
;                 __syncthreads();
;                 for (int o = F.tid; o < 5 * 256; o += NWAVES * 64) { const int r = o >> 8, ci = o & 255; float s = (F.ka->in[I_BMOD])[l * MODW + n0 + ci];
; #pragma unroll
;                     for (int w = 0; w < 8; ++w) s += RED[(w * 5 + r) * 256 + ci];
;                     MOD[((size_t)l * 5 + r) * MODW + n0 + ci] = s; }
	v_pk_fma_f32 v[18:19], v[24:25], v[50:51], v[18:19] op_sel_hi:[0,1,1]
	v_pk_fma_f32 v[20:21], v[24:25], v[52:53], v[20:21] op_sel_hi:[0,1,1]
	v_pk_fma_f32 v[14:15], v[32:33], v[50:51], v[14:15] op_sel_hi:[0,1,1]
	v_pk_fma_f32 v[16:17], v[32:33], v[52:53], v[16:17] op_sel_hi:[0,1,1]
	v_pk_fma_f32 v[10:11], v[106:107], v[50:51], v[10:11] op_sel_hi:[0,1,1]
	v_pk_fma_f32 v[12:13], v[106:107], v[52:53], v[12:13] op_sel_hi:[0,1,1]
	v_pk_fma_f32 v[6:7], v[108:109], v[50:51], v[6:7] op_sel_hi:[0,1,1]
	v_pk_fma_f32 v[8:9], v[108:109], v[52:53], v[8:9] op_sel_hi:[0,1,1]
	v_pk_fma_f32 v[2:3], v[110:111], v[50:51], v[2:3] op_sel_hi:[0,1,1]
	v_pk_fma_f32 v[4:5], v[110:111], v[52:53], v[4:5] op_sel_hi:[0,1,1]
	s_waitcnt vmcnt(2)
	v_pk_fma_f32 v[18:19], v[66:67], v[54:55], v[18:19] op_sel_hi:[0,1,1]
	v_pk_fma_f32 v[20:21], v[66:67], v[56:57], v[20:21] op_sel_hi:[0,1,1]
	v_pk_fma_f32 v[14:15], v[78:79], v[54:55], v[14:15] op_sel_hi:[0,1,1]
	v_pk_fma_f32 v[16:17], v[78:79], v[56:57], v[16:17] op_sel_hi:[0,1,1]
	v_pk_fma_f32 v[10:11], v[86:87], v[54:55], v[10:11] op_sel_hi:[0,1,1]
	v_pk_fma_f32 v[12:13], v[86:87], v[56:57], v[12:13] op_sel_hi:[0,1,1]
	v_pk_fma_f32 v[6:7], v[94:95], v[54:55], v[6:7] op_sel_hi:[0,1,1]
	v_pk_fma_f32 v[8:9], v[94:95], v[56:57], v[8:9] op_sel_hi:[0,1,1]
	v_pk_fma_f32 v[2:3], v[102:103], v[54:55], v[2:3] op_sel_hi:[0,1,1]
	v_pk_fma_f32 v[4:5], v[102:103], v[56:57], v[4:5] op_sel_hi:[0,1,1]
	s_waitcnt vmcnt(1)
	v_pk_fma_f32 v[18:19], v[66:67], v[58:59], v[18:19] op_sel:[1,0,0]
	v_pk_fma_f32 v[20:21], v[66:67], v[60:61], v[20:21] op_sel:[1,0,0]
	v_pk_fma_f32 v[14:15], v[78:79], v[58:59], v[14:15] op_sel:[1,0,0]
	v_pk_fma_f32 v[16:17], v[78:79], v[60:61], v[16:17] op_sel:[1,0,0]
	v_pk_fma_f32 v[10:11], v[86:87], v[58:59], v[10:11] op_sel:[1,0,0]
	v_pk_fma_f32 v[12:13], v[86:87], v[60:61], v[12:13] op_sel:[1,0,0]
	v_pk_fma_f32 v[6:7], v[94:95], v[58:59], v[6:7] op_sel:[1,0,0]
	v_pk_fma_f32 v[8:9], v[94:95], v[60:61], v[8:9] op_sel:[1,0,0]
	v_pk_fma_f32 v[2:3], v[102:103], v[58:59], v[2:3] op_sel:[1,0,0]
	v_pk_fma_f32 v[4:5], v[102:103], v[60:61], v[4:5] op_sel:[1,0,0]
	s_waitcnt vmcnt(0)
	v_pk_fma_f32 v[18:19], v[68:69], v[70:71], v[18:19] op_sel_hi:[0,1,1]
	v_pk_fma_f32 v[20:21], v[68:69], v[72:73], v[20:21] op_sel_hi:[0,1,1]
	v_pk_fma_f32 v[14:15], v[80:81], v[70:71], v[14:15] op_sel_hi:[0,1,1]
	v_pk_fma_f32 v[16:17], v[80:81], v[72:73], v[16:17] op_sel_hi:[0,1,1]
	v_pk_fma_f32 v[10:11], v[88:89], v[70:71], v[10:11] op_sel_hi:[0,1,1]
	v_pk_fma_f32 v[12:13], v[88:89], v[72:73], v[12:13] op_sel_hi:[0,1,1]
	v_pk_fma_f32 v[6:7], v[96:97], v[70:71], v[6:7] op_sel_hi:[0,1,1]
	v_pk_fma_f32 v[8:9], v[96:97], v[72:73], v[8:9] op_sel_hi:[0,1,1]
	v_pk_fma_f32 v[2:3], v[104:105], v[70:71], v[2:3] op_sel_hi:[0,1,1]
	v_pk_fma_f32 v[4:5], v[104:105], v[72:73], v[4:5] op_sel_hi:[0,1,1]
	v_pk_fma_f32 v[18:19], v[112:113], v[34:35], v[18:19] op_sel_hi:[0,1,1]
	v_pk_fma_f32 v[20:21], v[112:113], v[36:37], v[20:21] op_sel_hi:[0,1,1]
	v_pk_fma_f32 v[14:15], v[114:115], v[34:35], v[14:15] op_sel_hi:[0,1,1]
	v_pk_fma_f32 v[16:17], v[114:115], v[36:37], v[16:17] op_sel_hi:[0,1,1]
	v_pk_fma_f32 v[10:11], v[116:117], v[34:35], v[10:11] op_sel_hi:[0,1,1]
	v_pk_fma_f32 v[12:13], v[116:117], v[36:37], v[12:13] op_sel_hi:[0,1,1]
	v_pk_fma_f32 v[6:7], v[118:119], v[34:35], v[6:7] op_sel_hi:[0,1,1]
	v_pk_fma_f32 v[8:9], v[118:119], v[36:37], v[8:9] op_sel_hi:[0,1,1]
	v_pk_fma_f32 v[2:3], v[120:121], v[34:35], v[2:3] op_sel_hi:[0,1,1]
	v_pk_fma_f32 v[4:5], v[120:121], v[36:37], v[4:5] op_sel_hi:[0,1,1]
	s_cbranch_scc0 .LBB0_68
	ds_write_b128 v23, v[18:21] offset:40960
	ds_write_b128 v23, v[14:17] offset:41984
	ds_write_b128 v23, v[10:13] offset:43008
	ds_write_b128 v23, v[6:9] offset:44032
	ds_write_b128 v23, v[2:5] offset:45056
	s_waitcnt lgkmcnt(0)
	s_barrier
	s_and_saveexec_b64 s[12:13], vcc
	s_cbranch_execz .LBB0_66
	s_load_dwordx2 s[4:5], s[16:17], 0x28
	s_mul_i32 s19, s18, 0x3000
	s_add_i32 s33, s19, s10
	v_or_b32_sdwa v2, s33, v22 dst_sel:DWORD dst_unused:UNUSED_PAD src0_sel:DWORD src1_sel:BYTE_0
	v_ashrrev_i32_e32 v3, 31, v2
	s_mul_hi_i32 s19, s18, 5
	s_mul_i32 s18, s18, 5
	s_waitcnt lgkmcnt(0)
	v_lshl_add_u64 v[2:3], v[2:3], 2, s[4:5]
	v_lshl_add_u64 v[4:5], s[10:11], 2, v[26:27]
	s_mov_b64 s[10:11], 0
	v_mov_b32_e32 v6, v22
